# P0b int8 weight-transpose items: all 16 row loads (+gain loads) issued up front with counted vmcnt waits instead of a serialized 2-in-flight ladder
# baseline (speedup 1.0000x reference)
; #define LAS __attribute__((address_space(3)))
; __device__ __forceinline__ void p0_transpose_item_i8(const float* W, int K, int N, unsigned char* WT, int mode, LAS float* scr, int item, int lane, const float* gk, const float* cm) {
;     const int nblk = N / 64, kb = item / nblk, nb = item % nblk, k0 = 64 * kb, n0 = 64 * nb;
;     const int lr = lane >> 4, lc = (lane & 15) * 4;
; #pragma unroll 4
;     for (int i = 0; i < 16; ++i) { const int kk = 4 * i + lr; f32x4 v = *(const f32x4*)(W + (size_t)(k0 + kk) * N + n0 + lc); if (gk) v = v * gk[k0 + kk];
;         LAS float* d = scr + kk * 65 + lc; d[0] = v.x; d[1] = v.y; d[2] = v.z; d[3] = v.w; }
;     asm volatile("s_waitcnt lgkmcnt(0)" ::: "memory");
.LBB0_201:
	s_and_b64 vcc, exec, s[0:1]
	s_cbranch_vccnz .Lp0b_nogk
	global_load_dwordx4 v[80:83], v[22:23], off
	global_load_dword v160, v[20:21], off
	global_load_dwordx4 v[84:87], v[18:19], off
	global_load_dword v162, v[20:21], off offset:16
	global_load_dwordx4 v[88:91], v[16:17], off
	global_load_dword v164, v[20:21], off offset:32
	global_load_dwordx4 v[92:95], v[12:13], off
	global_load_dword v166, v[20:21], off offset:48
	s_mov_b32 s6, 0x58000
	s_mov_b32 s7, 0
	v_lshl_add_u64 v[152:153], v[22:23], 0, s[6:7]
	global_load_dwordx4 v[96:99], v[152:153], off
	global_load_dword v168, v[20:21], off offset:64
	v_lshl_add_u64 v[154:155], v[18:19], 0, s[6:7]
	global_load_dwordx4 v[100:103], v[154:155], off
	global_load_dword v170, v[20:21], off offset:80
	v_lshl_add_u64 v[156:157], v[16:17], 0, s[6:7]
	global_load_dwordx4 v[104:107], v[156:157], off
	global_load_dword v172, v[20:21], off offset:96
	v_lshl_add_u64 v[158:159], v[12:13], 0, s[6:7]
	global_load_dwordx4 v[108:111], v[158:159], off
	global_load_dword v174, v[20:21], off offset:112
	s_mov_b32 s6, 0xb0000
	v_lshl_add_u64 v[144:145], v[22:23], 0, s[6:7]
	global_load_dwordx4 v[112:115], v[144:145], off
	global_load_dword v176, v[20:21], off offset:128
	v_lshl_add_u64 v[146:147], v[18:19], 0, s[6:7]
	global_load_dwordx4 v[116:119], v[146:147], off
	global_load_dword v178, v[20:21], off offset:144
	v_lshl_add_u64 v[148:149], v[16:17], 0, s[6:7]
	global_load_dwordx4 v[120:123], v[148:149], off
	global_load_dword v180, v[20:21], off offset:160
	v_lshl_add_u64 v[150:151], v[12:13], 0, s[6:7]
	global_load_dwordx4 v[124:127], v[150:151], off
	global_load_dword v182, v[20:21], off offset:176
	s_mov_b32 s6, 0x108000
	v_lshl_add_u64 v[152:153], v[22:23], 0, s[6:7]
	global_load_dwordx4 v[128:131], v[152:153], off
	global_load_dword v184, v[20:21], off offset:192
	v_lshl_add_u64 v[154:155], v[18:19], 0, s[6:7]
	global_load_dwordx4 v[132:135], v[154:155], off
	global_load_dword v186, v[20:21], off offset:208
	v_lshl_add_u64 v[156:157], v[16:17], 0, s[6:7]
	global_load_dwordx4 v[136:139], v[156:157], off
	global_load_dword v188, v[20:21], off offset:224
	v_lshl_add_u64 v[158:159], v[12:13], 0, s[6:7]
	global_load_dwordx4 v[140:143], v[158:159], off
	global_load_dword v190, v[20:21], off offset:240
	s_waitcnt vmcnt(30)
	v_pk_mul_f32 v[80:81], v[80:81], v[160:161] op_sel_hi:[1,0]
	v_pk_mul_f32 v[82:83], v[82:83], v[160:161] op_sel_hi:[1,0]
	ds_write2_b32 v30, v80, v81 offset1:1
	ds_write2_b32 v30, v82, v83 offset0:2 offset1:3
	v_add_u32_e32 v193, 0x410, v30
	s_waitcnt vmcnt(28)
	v_pk_mul_f32 v[84:85], v[84:85], v[162:163] op_sel_hi:[1,0]
	v_pk_mul_f32 v[86:87], v[86:87], v[162:163] op_sel_hi:[1,0]
	ds_write2_b32 v193, v84, v85 offset1:1
	ds_write2_b32 v193, v86, v87 offset0:2 offset1:3
	v_add_u32_e32 v194, 0x820, v30
	s_waitcnt vmcnt(26)
	v_pk_mul_f32 v[88:89], v[88:89], v[164:165] op_sel_hi:[1,0]
	v_pk_mul_f32 v[90:91], v[90:91], v[164:165] op_sel_hi:[1,0]
	ds_write2_b32 v194, v88, v89 offset1:1
	ds_write2_b32 v194, v90, v91 offset0:2 offset1:3
	v_add_u32_e32 v195, 0xc30, v30
	s_waitcnt vmcnt(24)
	v_pk_mul_f32 v[92:93], v[92:93], v[166:167] op_sel_hi:[1,0]
	v_pk_mul_f32 v[94:95], v[94:95], v[166:167] op_sel_hi:[1,0]
	ds_write2_b32 v195, v92, v93 offset1:1
	ds_write2_b32 v195, v94, v95 offset0:2 offset1:3
	v_add_u32_e32 v196, 0x1040, v30
	s_waitcnt vmcnt(22)
	v_pk_mul_f32 v[96:97], v[96:97], v[168:169] op_sel_hi:[1,0]
	v_pk_mul_f32 v[98:99], v[98:99], v[168:169] op_sel_hi:[1,0]
	ds_write2_b32 v196, v96, v97 offset1:1
	ds_write2_b32 v196, v98, v99 offset0:2 offset1:3
	v_add_u32_e32 v197, 0x1450, v30
	s_waitcnt vmcnt(20)
	v_pk_mul_f32 v[100:101], v[100:101], v[170:171] op_sel_hi:[1,0]
	v_pk_mul_f32 v[102:103], v[102:103], v[170:171] op_sel_hi:[1,0]
	ds_write2_b32 v197, v100, v101 offset1:1
	ds_write2_b32 v197, v102, v103 offset0:2 offset1:3
	v_add_u32_e32 v198, 0x1860, v30
	s_waitcnt vmcnt(18)
	v_pk_mul_f32 v[104:105], v[104:105], v[172:173] op_sel_hi:[1,0]
	v_pk_mul_f32 v[106:107], v[106:107], v[172:173] op_sel_hi:[1,0]
	ds_write2_b32 v198, v104, v105 offset1:1
	ds_write2_b32 v198, v106, v107 offset0:2 offset1:3
	v_add_u32_e32 v199, 0x1c70, v30
	s_waitcnt vmcnt(16)
	v_pk_mul_f32 v[108:109], v[108:109], v[174:175] op_sel_hi:[1,0]
	v_pk_mul_f32 v[110:111], v[110:111], v[174:175] op_sel_hi:[1,0]
	ds_write2_b32 v199, v108, v109 offset1:1
	ds_write2_b32 v199, v110, v111 offset0:2 offset1:3
	v_add_u32_e32 v200, 0x2080, v30
	s_waitcnt vmcnt(14)
	v_pk_mul_f32 v[112:113], v[112:113], v[176:177] op_sel_hi:[1,0]
	v_pk_mul_f32 v[114:115], v[114:115], v[176:177] op_sel_hi:[1,0]
	ds_write2_b32 v200, v112, v113 offset1:1
	ds_write2_b32 v200, v114, v115 offset0:2 offset1:3
	v_add_u32_e32 v201, 0x2490, v30
	s_waitcnt vmcnt(12)
	v_pk_mul_f32 v[116:117], v[116:117], v[178:179] op_sel_hi:[1,0]
	v_pk_mul_f32 v[118:119], v[118:119], v[178:179] op_sel_hi:[1,0]
	ds_write2_b32 v201, v116, v117 offset1:1
	ds_write2_b32 v201, v118, v119 offset0:2 offset1:3
	v_add_u32_e32 v202, 0x28a0, v30
	s_waitcnt vmcnt(10)
	v_pk_mul_f32 v[120:121], v[120:121], v[180:181] op_sel_hi:[1,0]
	v_pk_mul_f32 v[122:123], v[122:123], v[180:181] op_sel_hi:[1,0]
	ds_write2_b32 v202, v120, v121 offset1:1
	ds_write2_b32 v202, v122, v123 offset0:2 offset1:3
	v_add_u32_e32 v203, 0x2cb0, v30
	s_waitcnt vmcnt(8)
	v_pk_mul_f32 v[124:125], v[124:125], v[182:183] op_sel_hi:[1,0]
	v_pk_mul_f32 v[126:127], v[126:127], v[182:183] op_sel_hi:[1,0]
	ds_write2_b32 v203, v124, v125 offset1:1
	ds_write2_b32 v203, v126, v127 offset0:2 offset1:3
	v_add_u32_e32 v204, 0x30c0, v30
	s_waitcnt vmcnt(6)
	v_pk_mul_f32 v[128:129], v[128:129], v[184:185] op_sel_hi:[1,0]
	v_pk_mul_f32 v[130:131], v[130:131], v[184:185] op_sel_hi:[1,0]
	ds_write2_b32 v204, v128, v129 offset1:1
	ds_write2_b32 v204, v130, v131 offset0:2 offset1:3
	v_add_u32_e32 v205, 0x34d0, v30
	s_waitcnt vmcnt(4)
	v_pk_mul_f32 v[132:133], v[132:133], v[186:187] op_sel_hi:[1,0]
	v_pk_mul_f32 v[134:135], v[134:135], v[186:187] op_sel_hi:[1,0]
	ds_write2_b32 v205, v132, v133 offset1:1
	ds_write2_b32 v205, v134, v135 offset0:2 offset1:3
	v_add_u32_e32 v206, 0x38e0, v30
	s_waitcnt vmcnt(2)
	v_pk_mul_f32 v[136:137], v[136:137], v[188:189] op_sel_hi:[1,0]
	v_pk_mul_f32 v[138:139], v[138:139], v[188:189] op_sel_hi:[1,0]
	ds_write2_b32 v206, v136, v137 offset1:1
	ds_write2_b32 v206, v138, v139 offset0:2 offset1:3
	v_add_u32_e32 v207, 0x3cf0, v30
	s_waitcnt vmcnt(0)
	v_pk_mul_f32 v[140:141], v[140:141], v[190:191] op_sel_hi:[1,0]
	v_pk_mul_f32 v[142:143], v[142:143], v[190:191] op_sel_hi:[1,0]
	ds_write2_b32 v207, v140, v141 offset1:1
	ds_write2_b32 v207, v142, v143 offset0:2 offset1:3
	s_branch .LBB0_209
; #define LAS __attribute__((address_space(3)))
; __device__ __forceinline__ void p0_transpose_item_i8(const float* W, int K, int N, unsigned char* WT, int mode, LAS float* scr, int item, int lane, const float* gk, const float* cm) {
;     ...
; #pragma unroll 4
;     for (int i = 0; i < 16; ++i) { const int kk = 4 * i + lr; f32x4 v = *(const f32x4*)(W + (size_t)(k0 + kk) * N + n0 + lc); if (gk) v = v * gk[k0 + kk];
;         LAS float* d = scr + kk * 65 + lc; d[0] = v.x; d[1] = v.y; d[2] = v.z; d[3] = v.w; }
.Lp0b_nogk:
	global_load_dwordx4 v[80:83], v[22:23], off
	global_load_dwordx4 v[84:87], v[18:19], off
	global_load_dwordx4 v[88:91], v[16:17], off
	global_load_dwordx4 v[92:95], v[12:13], off
	s_mov_b32 s6, 0x58000
	s_mov_b32 s7, 0
	v_lshl_add_u64 v[152:153], v[22:23], 0, s[6:7]
	global_load_dwordx4 v[96:99], v[152:153], off
	v_lshl_add_u64 v[154:155], v[18:19], 0, s[6:7]
	global_load_dwordx4 v[100:103], v[154:155], off
	v_lshl_add_u64 v[156:157], v[16:17], 0, s[6:7]
	global_load_dwordx4 v[104:107], v[156:157], off
	v_lshl_add_u64 v[158:159], v[12:13], 0, s[6:7]
	global_load_dwordx4 v[108:111], v[158:159], off
	s_mov_b32 s6, 0xb0000
	v_lshl_add_u64 v[144:145], v[22:23], 0, s[6:7]
	global_load_dwordx4 v[112:115], v[144:145], off
	v_lshl_add_u64 v[146:147], v[18:19], 0, s[6:7]
	global_load_dwordx4 v[116:119], v[146:147], off
	v_lshl_add_u64 v[148:149], v[16:17], 0, s[6:7]
	global_load_dwordx4 v[120:123], v[148:149], off
	v_lshl_add_u64 v[150:151], v[12:13], 0, s[6:7]
	global_load_dwordx4 v[124:127], v[150:151], off
	s_mov_b32 s6, 0x108000
	v_lshl_add_u64 v[152:153], v[22:23], 0, s[6:7]
	global_load_dwordx4 v[128:131], v[152:153], off
	v_lshl_add_u64 v[154:155], v[18:19], 0, s[6:7]
	global_load_dwordx4 v[132:135], v[154:155], off
	v_lshl_add_u64 v[156:157], v[16:17], 0, s[6:7]
	global_load_dwordx4 v[136:139], v[156:157], off
	v_lshl_add_u64 v[158:159], v[12:13], 0, s[6:7]
	global_load_dwordx4 v[140:143], v[158:159], off
	s_waitcnt vmcnt(15)
	ds_write2_b32 v30, v80, v81 offset1:1
	ds_write2_b32 v30, v82, v83 offset0:2 offset1:3
	v_add_u32_e32 v193, 0x410, v30
	s_waitcnt vmcnt(14)
	ds_write2_b32 v193, v84, v85 offset1:1
	ds_write2_b32 v193, v86, v87 offset0:2 offset1:3
	v_add_u32_e32 v194, 0x820, v30
	s_waitcnt vmcnt(13)
	ds_write2_b32 v194, v88, v89 offset1:1
	ds_write2_b32 v194, v90, v91 offset0:2 offset1:3
	v_add_u32_e32 v195, 0xc30, v30
	s_waitcnt vmcnt(12)
	ds_write2_b32 v195, v92, v93 offset1:1
	ds_write2_b32 v195, v94, v95 offset0:2 offset1:3
	v_add_u32_e32 v196, 0x1040, v30
	s_waitcnt vmcnt(11)
	ds_write2_b32 v196, v96, v97 offset1:1
	ds_write2_b32 v196, v98, v99 offset0:2 offset1:3
	v_add_u32_e32 v197, 0x1450, v30
	s_waitcnt vmcnt(10)
	ds_write2_b32 v197, v100, v101 offset1:1
	ds_write2_b32 v197, v102, v103 offset0:2 offset1:3
	v_add_u32_e32 v198, 0x1860, v30
	s_waitcnt vmcnt(9)
	ds_write2_b32 v198, v104, v105 offset1:1
	ds_write2_b32 v198, v106, v107 offset0:2 offset1:3
	v_add_u32_e32 v199, 0x1c70, v30
	s_waitcnt vmcnt(8)
	ds_write2_b32 v199, v108, v109 offset1:1
	ds_write2_b32 v199, v110, v111 offset0:2 offset1:3
	v_add_u32_e32 v200, 0x2080, v30
	s_waitcnt vmcnt(7)
	ds_write2_b32 v200, v112, v113 offset1:1
	ds_write2_b32 v200, v114, v115 offset0:2 offset1:3
	v_add_u32_e32 v201, 0x2490, v30
	s_waitcnt vmcnt(6)
	ds_write2_b32 v201, v116, v117 offset1:1
	ds_write2_b32 v201, v118, v119 offset0:2 offset1:3
	v_add_u32_e32 v202, 0x28a0, v30
	s_waitcnt vmcnt(5)
	ds_write2_b32 v202, v120, v121 offset1:1
	ds_write2_b32 v202, v122, v123 offset0:2 offset1:3
	v_add_u32_e32 v203, 0x2cb0, v30
	s_waitcnt vmcnt(4)
	ds_write2_b32 v203, v124, v125 offset1:1
	ds_write2_b32 v203, v126, v127 offset0:2 offset1:3
	v_add_u32_e32 v204, 0x30c0, v30
	s_waitcnt vmcnt(3)
	ds_write2_b32 v204, v128, v129 offset1:1
	ds_write2_b32 v204, v130, v131 offset0:2 offset1:3
	v_add_u32_e32 v205, 0x34d0, v30
	s_waitcnt vmcnt(2)
	ds_write2_b32 v205, v132, v133 offset1:1
	ds_write2_b32 v205, v134, v135 offset0:2 offset1:3
	v_add_u32_e32 v206, 0x38e0, v30
	s_waitcnt vmcnt(1)
	ds_write2_b32 v206, v136, v137 offset1:1
	ds_write2_b32 v206, v138, v139 offset0:2 offset1:3
	v_add_u32_e32 v207, 0x3cf0, v30
	s_waitcnt vmcnt(0)
	ds_write2_b32 v207, v140, v141 offset1:1
	ds_write2_b32 v207, v142, v143 offset0:2 offset1:3
